# P1 full-line stores + sample QK batched reads + prompt attention QKT: all 8 K-fragment LDS reads issued up front into dead registers, counted waits
# baseline (speedup 1.0000x reference)
.LBB0_505:
	s_add_i32 s64, s66, 2
	s_add_i32 s10, s55, 0
	v_add_u32_e32 v98, s10, v200
	ds_read_b128 v[130:133], v98
	ds_read_b128 v[134:137], v98 offset:8192
	v_add_u32_e32 v252, s10, v195
	v_add_u32_e32 v253, v252, v202
	ds_read_b128 v[228:231], v253
	ds_read_b128 v[232:235], v253 offset:8192
	v_add_u32_e32 v253, v252, v203
	ds_read_b128 v[236:239], v253
	ds_read_b128 v[240:243], v253 offset:8192
	v_add_u32_e32 v253, v252, v204
	ds_read_b128 v[244:247], v253
	ds_read_b128 v[248:251], v253 offset:8192
	s_cmp_lt_i32 s64, s84
	s_mov_b64 s[58:59], -1
	s_cbranch_scc1 .LBB0_507
	ds_read2_b32 v[114:115], v205 offset1:1
	ds_read2_b32 v[116:117], v205 offset0:2 offset1:3
	ds_read2_b32 v[118:119], v205 offset0:8 offset1:9
	ds_read2_b32 v[120:121], v205 offset0:10 offset1:11
	ds_read2_b32 v[122:123], v205 offset0:16 offset1:17
	ds_read2_b32 v[124:125], v205 offset0:18 offset1:19
	ds_read2_b32 v[126:127], v205 offset0:24 offset1:25
	ds_read2_b32 v[128:129], v205 offset0:26 offset1:27
	ds_read2_b32 v[98:99], v205 offset0:32 offset1:33
	ds_read2_b32 v[100:101], v205 offset0:34 offset1:35
	ds_read2_b32 v[102:103], v205 offset0:40 offset1:41
	ds_read2_b32 v[104:105], v205 offset0:42 offset1:43
	ds_read2_b32 v[106:107], v205 offset0:48 offset1:49
	ds_read2_b32 v[108:109], v205 offset0:50 offset1:51
	ds_read2_b32 v[110:111], v205 offset0:56 offset1:57
	ds_read2_b32 v[112:113], v205 offset0:58 offset1:59
	s_waitcnt lgkmcnt(8)
	v_mfma_f32_32x32x16_bf16 v[114:129], v[130:133], v[174:177], v[114:129]
	s_mov_b64 s[58:59], 0
	s_waitcnt lgkmcnt(0)
	v_mfma_f32_32x32x16_bf16 v[98:113], v[134:137], v[174:177], v[98:113]
.LBB0_507:
	s_andn2_b64 vcc, exec, s[58:59]
	s_cbranch_vccnz .LBB0_509
	s_waitcnt lgkmcnt(7)
	v_mfma_f32_32x32x16_bf16 v[114:129], v[130:133], v[174:177], v[82:97]
	s_waitcnt lgkmcnt(6)
	v_mfma_f32_32x32x16_bf16 v[98:113], v[134:137], v[174:177], v[82:97]
.LBB0_509:
	s_add_i32 vcc_lo, s66, 3
	s_waitcnt lgkmcnt(5)
	v_mfma_f32_32x32x16_bf16 v[114:129], v[228:231], v[170:173], v[114:129]
	s_add_i32 s10, s66, 4
	s_cmp_lt_u32 s64, s34
	s_cselect_b32 s10, s10, s2
	s_lshl_b64 s[58:59], s[10:11], 17
	s_add_u32 s60, s0, s58
	s_addc_u32 s61, s1, s59
	s_waitcnt lgkmcnt(4)
	v_mfma_f32_32x32x16_bf16 v[98:113], v[232:235], v[170:173], v[98:113]
	s_add_u32 s58, s56, s58
	s_addc_u32 s59, s57, s59
	s_waitcnt lgkmcnt(3)
	v_mfma_f32_32x32x16_bf16 v[114:129], v[236:239], v[166:169], v[114:129]
	v_cvt_pk_bf16_f32 v146, v146, v147
	v_cvt_pk_bf16_f32 v147, v148, v149
	v_cvt_pk_bf16_f32 v148, v150, v151
	v_cvt_pk_bf16_f32 v149, v152, v153
	s_nop 0
	v_permlane32_swap_b32_e32 v146, v148
	s_waitcnt lgkmcnt(2)
	v_mfma_f32_32x32x16_bf16 v[98:113], v[240:243], v[166:169], v[98:113]
	v_cvt_pk_bf16_f32 v134, v154, v155
	v_cvt_pk_bf16_f32 v135, v156, v157
	v_cvt_pk_bf16_f32 v136, v158, v221
	v_cvt_pk_bf16_f32 v137, v222, v223
	v_permlane32_swap_b32_e32 v147, v149
	v_permlane32_swap_b32_e32 v134, v136
	s_waitcnt lgkmcnt(1)
	v_mfma_f32_32x32x16_bf16 v[114:129], v[244:247], v[162:165], v[114:129]
	v_cvt_pk_bf16_f32 v130, v159, v160
	v_cvt_pk_bf16_f32 v131, v161, v199
	v_cvt_pk_bf16_f32 v132, v224, v225
	v_cvt_pk_bf16_f32 v133, v226, v227
	v_cvt_pk_bf16_f32 v138, v138, v139
	v_cvt_pk_bf16_f32 v139, v140, v141
	v_cvt_pk_bf16_f32 v140, v142, v143
	s_waitcnt lgkmcnt(0)
	v_mfma_f32_32x32x16_bf16 v[98:113], v[248:251], v[162:165], v[98:113]
	v_cvt_pk_bf16_f32 v141, v144, v145
	v_permlane32_swap_b32_e32 v135, v137
	v_permlane32_swap_b32_e32 v130, v132
	v_permlane32_swap_b32_e32 v131, v133
	v_permlane32_swap_b32_e32 v138, v140
	v_permlane32_swap_b32_e32 v139, v141
	v_add_u32_e32 v206, s14, v220
	ds_read_b64_tr_b16 v[142:143], v206 offset:0
	ds_read_b64_tr_b16 v[144:145], v206 offset:0x800
	ds_read_b64_tr_b16 v[150:151], v206 offset:0x1000
	ds_read_b64_tr_b16 v[152:153], v206 offset:0x1800
	ds_read_b64_tr_b16 v[154:155], v206 offset:0x2000
	ds_read_b64_tr_b16 v[156:157], v206 offset:0x2800
	ds_read_b64_tr_b16 v[158:159], v206 offset:0x3000
	ds_read_b64_tr_b16 v[160:161], v206 offset:0x3800
	v_mov_b64_e32 v[180:181], s[6:7]
	v_mov_b64_e32 v[178:179], s[4:5]
	s_nop 1
	v_mfma_f32_32x32x16_bf16 v[2:17], v[146:149], v[178:181], v[2:17]
	v_mfma_f32_32x32x16_bf16 v[2:17], v[134:137], v[178:181], v[2:17]
	v_mfma_f32_32x32x16_bf16 v[2:17], v[130:133], v[178:181], v[2:17]
	v_mfma_f32_32x32x16_bf16 v[2:17], v[138:141], v[178:181], v[2:17]
	ds_read_b64_tr_b16 v[178:179], v206 offset:0x200
	ds_read_b64_tr_b16 v[180:181], v206 offset:0xa00
	ds_read_b64_tr_b16 v[182:183], v206 offset:0x1200
	ds_read_b64_tr_b16 v[184:185], v206 offset:0x1a00
	ds_read_b64_tr_b16 v[186:187], v206 offset:0x2200
	ds_read_b64_tr_b16 v[188:189], v206 offset:0x2a00
	ds_read_b64_tr_b16 v[190:191], v206 offset:0x3200
	ds_read_b64_tr_b16 v[192:193], v206 offset:0x3a00
	s_waitcnt lgkmcnt(8)
	v_mfma_f32_32x32x16_bf16 v[18:33], v[146:149], v[142:145], v[18:33]
	v_mfma_f32_32x32x16_bf16 v[18:33], v[134:137], v[150:153], v[18:33]
	v_mfma_f32_32x32x16_bf16 v[18:33], v[130:133], v[154:157], v[18:33]
	v_mfma_f32_32x32x16_bf16 v[18:33], v[138:141], v[158:161], v[18:33]
	v_lshl_add_u64 v[142:143], s[60:61], 0, v[210:211]
	s_add_i32 s10, s65, s92
	s_mov_b32 s14, m0
	s_mov_b32 m0, s10
	s_nop 0
	global_load_lds_dwordx4 v[142:143], off
	s_mov_b32 m0, s14
	ds_read_b64_tr_b16 v[142:143], v206 offset:0x400
	ds_read_b64_tr_b16 v[144:145], v206 offset:0xc00
	ds_read_b64_tr_b16 v[150:151], v206 offset:0x1400
	ds_read_b64_tr_b16 v[152:153], v206 offset:0x1c00
	ds_read_b64_tr_b16 v[154:155], v206 offset:0x2400
	ds_read_b64_tr_b16 v[156:157], v206 offset:0x2c00
	ds_read_b64_tr_b16 v[158:159], v206 offset:0x3400
	ds_read_b64_tr_b16 v[160:161], v206 offset:0x3c00
	s_waitcnt lgkmcnt(8)
	v_mfma_f32_32x32x16_bf16 v[66:81], v[146:149], v[178:181], v[66:81]
	v_mfma_f32_32x32x16_bf16 v[66:81], v[134:137], v[182:185], v[66:81]
	v_mfma_f32_32x32x16_bf16 v[66:81], v[130:133], v[186:189], v[66:81]
	v_mfma_f32_32x32x16_bf16 v[66:81], v[138:141], v[190:193], v[66:81]
	v_mov_b32_e32 v199, v211
	v_lshl_add_u64 v[178:179], s[60:61], 0, v[198:199]
	s_addk_i32 s10, 0x400
	s_mov_b32 s14, m0
	s_mov_b32 m0, s10
	s_nop 0
	global_load_lds_dwordx4 v[178:179], off
	s_mov_b32 m0, s14
	ds_read_b64_tr_b16 v[178:179], v206 offset:0x600
	ds_read_b64_tr_b16 v[180:181], v206 offset:0xe00
	ds_read_b64_tr_b16 v[182:183], v206 offset:0x1600
	ds_read_b64_tr_b16 v[184:185], v206 offset:0x1e00
	ds_read_b64_tr_b16 v[186:187], v206 offset:0x2600
	ds_read_b64_tr_b16 v[188:189], v206 offset:0x2e00
	ds_read_b64_tr_b16 v[190:191], v206 offset:0x3600
	ds_read_b64_tr_b16 v[192:193], v206 offset:0x3e00
	s_waitcnt lgkmcnt(8)
	v_mfma_f32_32x32x16_bf16 v[50:65], v[146:149], v[142:145], v[50:65]
	v_mfma_f32_32x32x16_bf16 v[50:65], v[134:137], v[150:153], v[50:65]
	v_mfma_f32_32x32x16_bf16 v[50:65], v[130:133], v[154:157], v[50:65]
	v_mfma_f32_32x32x16_bf16 v[50:65], v[138:141], v[158:161], v[50:65]
	v_lshl_add_u64 v[142:143], v[196:197], 1, s[58:59]
	s_add_i32 s10, s65, s93
	s_mov_b32 s14, m0
	s_mov_b32 m0, s10
	s_nop 0
	global_load_lds_dwordx4 v[142:143], off
	s_mov_b32 m0, s14
	s_waitcnt lgkmcnt(0)
	v_mfma_f32_32x32x16_bf16 v[34:49], v[146:149], v[178:181], v[34:49]
	v_mfma_f32_32x32x16_bf16 v[34:49], v[134:137], v[182:185], v[34:49]
	v_mfma_f32_32x32x16_bf16 v[34:49], v[130:133], v[186:189], v[34:49]
	v_mfma_f32_32x32x16_bf16 v[34:49], v[138:141], v[190:193], v[34:49]
	v_lshl_add_u64 v[130:131], v[142:143], 0, s[50:51]
	s_addk_i32 s10, 0x400
	s_mov_b32 s14, m0
	s_mov_b32 m0, s10
	s_nop 0
	global_load_lds_dwordx4 v[130:131], off
	s_mov_b32 m0, s14
	s_waitcnt vmcnt(4) lgkmcnt(0)
	s_barrier
	s_add_i32 s10, s70, 0
	v_add_u32_e32 v130, s10, v200
	ds_read_b128 v[178:181], v130
	ds_read_b128 v[182:185], v130 offset:8192
	v_add_u32_e32 v252, s10, v195
	v_add_u32_e32 v253, v252, v202
	ds_read_b128 v[228:231], v253
	ds_read_b128 v[232:235], v253 offset:8192
	v_add_u32_e32 v253, v252, v203
	ds_read_b128 v[236:239], v253
	ds_read_b128 v[240:243], v253 offset:8192
	v_add_u32_e32 v253, v252, v204
	ds_read_b128 v[244:247], v253
	ds_read_b128 v[248:251], v253 offset:8192
	s_cmp_lt_i32 vcc_lo, s84
	s_mov_b64 s[58:59], -1
	s_cbranch_scc1 .LBB0_511
	ds_read2_b32 v[146:147], v205 offset0:64 offset1:65
	ds_read2_b32 v[148:149], v205 offset0:66 offset1:67
	ds_read2_b32 v[150:151], v205 offset0:72 offset1:73
	ds_read2_b32 v[152:153], v205 offset0:74 offset1:75
	ds_read2_b32 v[154:155], v205 offset0:80 offset1:81
	ds_read2_b32 v[156:157], v205 offset0:82 offset1:83
	ds_read2_b32 v[158:159], v205 offset0:88 offset1:89
	ds_read2_b32 v[160:161], v205 offset0:90 offset1:91
	ds_read2_b32 v[130:131], v205 offset0:96 offset1:97
	ds_read2_b32 v[132:133], v205 offset0:98 offset1:99
	ds_read2_b32 v[134:135], v205 offset0:104 offset1:105
	ds_read2_b32 v[136:137], v205 offset0:106 offset1:107
	ds_read2_b32 v[138:139], v205 offset0:112 offset1:113
	ds_read2_b32 v[140:141], v205 offset0:114 offset1:115
	ds_read2_b32 v[142:143], v205 offset0:120 offset1:121
	ds_read2_b32 v[144:145], v205 offset0:122 offset1:123
	s_waitcnt lgkmcnt(8)
	v_mfma_f32_32x32x16_bf16 v[146:161], v[178:181], v[174:177], v[146:161]
	s_mov_b64 s[58:59], 0
	s_waitcnt lgkmcnt(0)
	v_mfma_f32_32x32x16_bf16 v[130:145], v[182:185], v[174:177], v[130:145]
.LBB0_511:
	s_andn2_b64 vcc, exec, s[58:59]
	s_cbranch_vccnz .LBB0_513
	s_waitcnt lgkmcnt(7)
	v_mfma_f32_32x32x16_bf16 v[146:161], v[178:181], v[174:177], v[82:97]
	s_waitcnt lgkmcnt(6)
	v_mfma_f32_32x32x16_bf16 v[130:145], v[182:185], v[174:177], v[82:97]
.LBB0_513:
	s_add_i32 s10, s65, 0x8000
	s_cmp_lg_u32 s65, 0x18000
	s_cselect_b32 vcc_lo, s10, 0
	s_add_i32 s10, s66, 5
	s_cmp_lt_i32 s64, s3
	s_waitcnt lgkmcnt(5)
	v_mfma_f32_32x32x16_bf16 v[146:161], v[228:231], v[170:173], v[146:161]
	s_cselect_b32 s10, s10, s2
	s_lshl_b64 s[58:59], s[10:11], 17
	s_add_u32 s60, s0, s58
	s_addc_u32 s61, s1, s59
	s_add_u32 s58, s56, s58
	v_exp_f32_e32 v114, v114
	v_exp_f32_e32 v115, v115
	s_waitcnt lgkmcnt(3)
	v_mfma_f32_32x32x16_bf16 v[146:161], v[236:239], v[166:169], v[146:161]
	v_exp_f32_e32 v116, v116
	v_exp_f32_e32 v117, v117
	v_exp_f32_e32 v118, v118
	v_exp_f32_e32 v119, v119
	v_exp_f32_e32 v120, v120
	v_exp_f32_e32 v121, v121
	v_mfma_f32_32x32x16_bf16 v[130:145], v[232:235], v[170:173], v[130:145]
	v_exp_f32_e32 v122, v122
	v_exp_f32_e32 v123, v123
	v_exp_f32_e32 v124, v124
	v_exp_f32_e32 v125, v125
	v_exp_f32_e32 v126, v126
	v_exp_f32_e32 v127, v127
	s_waitcnt lgkmcnt(2)
	v_mfma_f32_32x32x16_bf16 v[130:145], v[240:243], v[166:169], v[130:145]
	v_exp_f32_e32 v128, v128
	v_exp_f32_e32 v129, v129
	v_exp_f32_e32 v98, v98
	v_exp_f32_e32 v99, v99
	v_exp_f32_e32 v100, v100
	v_exp_f32_e32 v101, v101
	s_waitcnt lgkmcnt(1)
	v_mfma_f32_32x32x16_bf16 v[146:161], v[244:247], v[162:165], v[146:161]
	v_exp_f32_e32 v102, v102
	v_exp_f32_e32 v103, v103
	v_exp_f32_e32 v104, v104
	v_exp_f32_e32 v105, v105
	v_exp_f32_e32 v106, v106
	v_exp_f32_e32 v107, v107
	v_exp_f32_e32 v108, v108
	s_waitcnt lgkmcnt(0)
; #define EXPALL(X0, X1) do { _Pragma("unroll") for (int r = 0; r < 16; ++r) { EX2(X0, r); EX2(X1, r); } } while (0)
; #define ROT() do { s_prev = s_cur; s_cur = s_next; s_next = s_nn; s_nn = (s_nn == 3 * P_SLOT) ? 0 : s_nn + P_SLOT; } while (0)
; __device__ __forceinline__ void attn_prompt(Frame& F, int b, int h, int qb, float lam, float mshift) {
;     ...
;     int s_prev = 0, s_cur = 0, s_next = P_SLOT, s_nn = 2 * P_SLOT;
;     ...
;     asm volatile("s_waitcnt vmcnt(0)" ::: "memory"); __syncthreads();
;     { const float cf = TB[63];
; #pragma unroll
;       for (int r = 0; r < 16; ++r) CF[r] = cf; }
;     { const int j2 = (2 < NT) ? 2 : NT - 1; DMA_TILE(j2, 2 * P_SLOT); }
;     QKT(pA0, pA1, 0, 0); EXPALL(pA0, pA1);
;     ROT();
	v_mfma_f32_32x32x16_bf16 v[130:145], v[248:251], v[162:165], v[130:145]
	v_exp_f32_e32 v109, v109
	v_exp_f32_e32 v110, v110
	v_exp_f32_e32 v111, v111
	v_exp_f32_e32 v112, v112
	v_exp_f32_e32 v113, v113
	s_addc_u32 s59, s57, s59
	s_add_i32 s71, vcc_lo, s92
	s_add_i32 s66, vcc_lo, s93
	s_add_i32 vcc_hi, s71, 0x400
	s_add_i32 s14, s66, 0x400
	s_add_i32 s10, vcc_lo, 0x8000
	s_cmp_lg_u32 vcc_lo, 0x18000
	s_cselect_b32 s10, s10, 0
	v_cvt_pk_bf16_f32 v190, v114, v115
	v_cvt_pk_bf16_f32 v191, v116, v117
	v_cvt_pk_bf16_f32 v192, v118, v119
	v_cvt_pk_bf16_f32 v193, v120, v121
	v_cvt_pk_bf16_f32 v186, v122, v123
	v_cvt_pk_bf16_f32 v187, v124, v125
	v_cvt_pk_bf16_f32 v188, v126, v127
	v_cvt_pk_bf16_f32 v189, v128, v129
	v_cvt_pk_bf16_f32 v182, v98, v99
	v_cvt_pk_bf16_f32 v183, v100, v101
	v_cvt_pk_bf16_f32 v184, v102, v103
	v_cvt_pk_bf16_f32 v185, v104, v105
	v_cvt_pk_bf16_f32 v178, v106, v107
	v_cvt_pk_bf16_f32 v179, v108, v109
	v_cvt_pk_bf16_f32 v180, v110, v111
	v_cvt_pk_bf16_f32 v181, v112, v113
	s_cmp_ge_i32 s64, s3
	v_permlane32_swap_b32_e32 v190, v192
	v_permlane32_swap_b32_e32 v191, v193
	v_permlane32_swap_b32_e32 v186, v188
	v_permlane32_swap_b32_e32 v187, v189
	v_permlane32_swap_b32_e32 v182, v184
	v_permlane32_swap_b32_e32 v183, v185
	v_permlane32_swap_b32_e32 v178, v180
	v_permlane32_swap_b32_e32 v179, v181
	v_add_u32_e32 v254, s55, v220
	ds_read_b64_tr_b16 v[206:207], v254 offset:0
	ds_read_b64_tr_b16 v[208:209], v254 offset:0x800
	ds_read_b64_tr_b16 v[222:223], v254 offset:0x1000
	ds_read_b64_tr_b16 v[224:225], v254 offset:0x1800
	ds_read_b64_tr_b16 v[226:227], v254 offset:0x2000
	ds_read_b64_tr_b16 v[228:229], v254 offset:0x2800
	ds_read_b64_tr_b16 v[230:231], v254 offset:0x3000
	ds_read_b64_tr_b16 v[232:233], v254 offset:0x3800
	v_mov_b64_e32 v[236:237], s[6:7]
	v_mov_b64_e32 v[234:235], s[4:5]
	s_nop 1
	v_mfma_f32_32x32x16_bf16 v[2:17], v[190:193], v[234:237], v[2:17]
	v_mfma_f32_32x32x16_bf16 v[2:17], v[186:189], v[234:237], v[2:17]
	v_mfma_f32_32x32x16_bf16 v[2:17], v[182:185], v[234:237], v[2:17]
	v_mfma_f32_32x32x16_bf16 v[2:17], v[178:181], v[234:237], v[2:17]
	ds_read_b64_tr_b16 v[234:235], v254 offset:0x200
	ds_read_b64_tr_b16 v[236:237], v254 offset:0xa00
	ds_read_b64_tr_b16 v[238:239], v254 offset:0x1200
	ds_read_b64_tr_b16 v[240:241], v254 offset:0x1a00
	ds_read_b64_tr_b16 v[242:243], v254 offset:0x2200
	ds_read_b64_tr_b16 v[244:245], v254 offset:0x2a00
	ds_read_b64_tr_b16 v[246:247], v254 offset:0x3200
	ds_read_b64_tr_b16 v[248:249], v254 offset:0x3a00
	s_waitcnt lgkmcnt(8)
	v_mfma_f32_32x32x16_bf16 v[18:33], v[190:193], v[206:209], v[18:33]
	v_exp_f32_e32 v146, v146
	v_exp_f32_e32 v147, v147
	v_mfma_f32_32x32x16_bf16 v[18:33], v[186:189], v[222:225], v[18:33]
	v_exp_f32_e32 v148, v148
	v_exp_f32_e32 v149, v149
	v_mfma_f32_32x32x16_bf16 v[18:33], v[182:185], v[226:229], v[18:33]
	v_exp_f32_e32 v150, v150
	v_exp_f32_e32 v151, v151
	v_mfma_f32_32x32x16_bf16 v[18:33], v[178:181], v[230:233], v[18:33]
	v_exp_f32_e32 v152, v152
	v_exp_f32_e32 v153, v153
	v_lshl_add_u64 v[206:207], s[60:61], 0, v[210:211]
	s_mov_b32 s55, m0
	s_mov_b32 m0, s71
	s_nop 0
	global_load_lds_dwordx4 v[206:207], off
	s_mov_b32 m0, s55
	ds_read_b64_tr_b16 v[206:207], v254 offset:0x400
	ds_read_b64_tr_b16 v[208:209], v254 offset:0xc00
	ds_read_b64_tr_b16 v[224:225], v254 offset:0x1400
	ds_read_b64_tr_b16 v[226:227], v254 offset:0x1c00
	ds_read_b64_tr_b16 v[228:229], v254 offset:0x2400
	ds_read_b64_tr_b16 v[230:231], v254 offset:0x2c00
	ds_read_b64_tr_b16 v[250:251], v254 offset:0x3400
	ds_read_b64_tr_b16 v[252:253], v254 offset:0x3c00
	s_waitcnt lgkmcnt(8)
	v_mfma_f32_32x32x16_bf16 v[66:81], v[190:193], v[234:237], v[66:81]
	v_exp_f32_e32 v154, v154
	v_exp_f32_e32 v155, v155
	v_mfma_f32_32x32x16_bf16 v[66:81], v[186:189], v[238:241], v[66:81]
	v_exp_f32_e32 v156, v156
	v_exp_f32_e32 v157, v157
	v_mfma_f32_32x32x16_bf16 v[66:81], v[182:185], v[242:245], v[66:81]
	v_exp_f32_e32 v158, v158
	v_exp_f32_e32 v221, v159
	v_mfma_f32_32x32x16_bf16 v[66:81], v[178:181], v[246:249], v[66:81]
	v_exp_f32_e32 v222, v160
	v_exp_f32_e32 v223, v161
	v_mov_b32_e32 v199, v211
	v_lshl_add_u64 v[160:161], s[60:61], 0, v[198:199]
	s_mov_b32 s55, m0
	s_mov_b32 m0, vcc_hi
	s_nop 0
	global_load_lds_dwordx4 v[160:161], off
	s_mov_b32 m0, s55
	ds_read_b64_tr_b16 v[232:233], v254 offset:0x600
	ds_read_b64_tr_b16 v[234:235], v254 offset:0xe00
	ds_read_b64_tr_b16 v[236:237], v254 offset:0x1600
	ds_read_b64_tr_b16 v[238:239], v254 offset:0x1e00
	ds_read_b64_tr_b16 v[240:241], v254 offset:0x2600
	ds_read_b64_tr_b16 v[242:243], v254 offset:0x2e00
	ds_read_b64_tr_b16 v[244:245], v254 offset:0x3600
	ds_read_b64_tr_b16 v[246:247], v254 offset:0x3e00
	s_waitcnt lgkmcnt(8)
	v_mfma_f32_32x32x16_bf16 v[50:65], v[190:193], v[206:209], v[50:65]
	v_exp_f32_e32 v159, v130
	v_exp_f32_e32 v160, v131
	v_mfma_f32_32x32x16_bf16 v[50:65], v[186:189], v[224:227], v[50:65]
	v_exp_f32_e32 v161, v132
	v_exp_f32_e32 v199, v133
	v_mfma_f32_32x32x16_bf16 v[50:65], v[182:185], v[228:231], v[50:65]
	v_exp_f32_e32 v224, v134
	v_exp_f32_e32 v225, v135
	v_mfma_f32_32x32x16_bf16 v[50:65], v[178:181], v[250:253], v[50:65]
	v_exp_f32_e32 v226, v136
	v_exp_f32_e32 v227, v137
	v_lshl_add_u64 v[130:131], v[196:197], 1, s[58:59]
	s_mov_b32 s55, m0
	s_mov_b32 m0, s66
	s_nop 0
	global_load_lds_dwordx4 v[130:131], off
	s_mov_b32 m0, s55
	s_waitcnt lgkmcnt(0)
	v_mfma_f32_32x32x16_bf16 v[34:49], v[190:193], v[232:235], v[34:49]
	v_exp_f32_e32 v138, v138
	v_exp_f32_e32 v139, v139
	v_mfma_f32_32x32x16_bf16 v[34:49], v[186:189], v[236:239], v[34:49]
	v_exp_f32_e32 v140, v140
	v_exp_f32_e32 v141, v141
	v_mfma_f32_32x32x16_bf16 v[34:49], v[182:185], v[240:243], v[34:49]
	v_exp_f32_e32 v142, v142
	v_exp_f32_e32 v143, v143
	v_mfma_f32_32x32x16_bf16 v[34:49], v[178:181], v[244:247], v[34:49]
	v_exp_f32_e32 v144, v144
	v_exp_f32_e32 v145, v145
	v_lshl_add_u64 v[130:131], v[130:131], 0, s[50:51]
	s_mov_b32 s55, m0
	s_mov_b32 m0, s14
	s_nop 0
	global_load_lds_dwordx4 v[130:131], off
	s_mov_b32 m0, s55
	s_waitcnt vmcnt(4) lgkmcnt(0)
	s_barrier
	v_add_u32_e32 v205, 0x200, v205
	s_cbranch_scc1 .LBB0_515
	s_mov_b32 s66, s64
	s_mov_b32 s14, s70
	s_mov_b32 s55, s65
	s_mov_b32 s70, vcc_lo
	s_mov_b32 s65, s10
	s_branch .LBB0_505
